# adds: P4 per-group scan issues a_log and both DT loads together (one round trip instead of two)
# baseline (speedup 1.0000x reference)
.LBB0_825:
	s_add_i32 s0, s22, s2
	s_mov_b32 s1, s23
	s_lshl_b64 s[0:1], s[0:1], 2
	s_add_u32 s12, s4, s0
	s_addc_u32 s13, s5, s1
	v_lshl_add_u64 v[4:5], v[198:199], 0, s[0:1]
	global_load_dword v0, v107, s[12:13]
	global_load_dword v2, v[4:5], off
	global_load_dword v3, v[4:5], off offset:48
	s_nop 0
	v_add_u32_e32 v5, -1, v195
	s_waitcnt vmcnt(2)
	v_mul_f32_e32 v0, 0x3fb8aa3b, v0
	v_exp_f32_e32 v4, v0
	v_and_b32_e32 v1, 64, v195
	v_cmp_lt_i32_e32 vcc, v5, v1
	s_waitcnt vmcnt(1)
	v_mul_f32_e32 v0, v2, v4
	v_cndmask_b32_e32 v5, v5, v195, vcc
	s_waitcnt vmcnt(0)
	v_fma_f32 v0, v3, -v4, -v0
	v_lshlrev_b32_e32 v5, 2, v5
	ds_bpermute_b32 v5, v5, v0
	s_waitcnt lgkmcnt(0)
	v_add_f32_e32 v5, v0, v5
	v_cndmask_b32_e64 v0, v5, v0, s[56:57]
	v_add_u32_e32 v5, -2, v195
	v_cmp_lt_i32_e32 vcc, v5, v1
	s_nop 1
	v_cndmask_b32_e32 v5, v5, v195, vcc
	v_lshlrev_b32_e32 v5, 2, v5
	ds_bpermute_b32 v5, v5, v0
	s_waitcnt lgkmcnt(0)
	v_add_f32_e32 v5, v0, v5
	v_cndmask_b32_e64 v0, v5, v0, s[58:59]
	v_add_u32_e32 v5, -4, v195
	v_cmp_lt_i32_e32 vcc, v5, v1
	s_nop 1
	v_cndmask_b32_e32 v5, v5, v195, vcc
	v_lshlrev_b32_e32 v5, 2, v5
	ds_bpermute_b32 v5, v5, v0
	s_waitcnt lgkmcnt(0)
	v_add_f32_e32 v5, v0, v5
	v_cndmask_b32_e64 v0, v5, v0, s[60:61]
	v_add_u32_e32 v5, -8, v195
	v_cmp_lt_i32_e32 vcc, v5, v1
	s_nop 1
	v_cndmask_b32_e32 v5, v5, v195, vcc
	v_lshlrev_b32_e32 v5, 2, v5
	ds_bpermute_b32 v5, v5, v0
	s_waitcnt lgkmcnt(0)
	v_add_f32_e32 v5, v0, v5
	v_cndmask_b32_e64 v0, v5, v0, s[62:63]
	v_add_u32_e32 v5, -16, v195
	v_cmp_lt_i32_e32 vcc, v5, v1
	s_nop 1
	v_cndmask_b32_e32 v5, v5, v195, vcc
	v_lshlrev_b32_e32 v5, 2, v5
	ds_bpermute_b32 v5, v5, v0
	s_waitcnt lgkmcnt(0)
	v_add_f32_e32 v5, v0, v5
	v_cndmask_b32_e64 v0, v5, v0, s[64:65]
	v_subrev_u32_e32 v5, 32, v195
	v_cmp_lt_i32_e32 vcc, v5, v1
	s_nop 1
	v_cndmask_b32_e32 v1, v5, v195, vcc
	v_lshlrev_b32_e32 v1, 2, v1
	ds_bpermute_b32 v1, v1, v0
	s_waitcnt lgkmcnt(0)
	v_add_f32_e32 v1, v0, v1
	v_cndmask_b32_e64 v1, v1, v0, s[66:67]
	v_fma_f32 v0, v3, v4, v1
	ds_write_b64 v113, v[2:3]
	ds_write_b64 v115, v[0:1]
	s_mul_i32 s12, s16, 0xc0
	s_and_saveexec_b64 s[0:1], s[54:55]
	s_xor_b64 s[82:83], exec, s[0:1]
	s_cbranch_execz .LBB0_824
